# v-sweep: slice-change gamma/beta reload without the vmcnt(0) drain (older loads are covered by the loop's counted waits)
# baseline (speedup 1.0000x reference)
.LBB0_1139:
	s_and_b32 s39, s41, 31
	v_or_b32_e32 v138, s39, v74
	s_and_b32 s18, s6, 0xf80
	s_lshr_b32 s11, s41, 5
	s_cmp_lg_u32 s39, 0
	s_cbranch_scc1 .Lvsw_skip_gb
	v_readlane_b32 s100, v255, 10
	v_readlane_b32 s101, v255, 11
	v_readlane_b32 s98, v255, 12
	v_readlane_b32 s99, v255, 13
	v_lshl_or_b32 v250, s11, 7, v34
	v_lshlrev_b32_e32 v250, 2, v250
	s_nop 4
	global_load_dwordx2 v[246:247], v250, s[100:101]
	global_load_dwordx2 v[248:249], v250, s[98:99]
.Lvsw_skip_gb:
	v_readlane_b32 s100, v252, s39
	v_readlane_b32 s101, v253, s39
	v_ashrrev_i32_e32 v139, 31, v138
	v_lshl_add_u32 v173, s18, 1, v145
	s_lshl_b32 s18, s11, 7
	v_lshlrev_b64 v[138:139], 10, v[138:139]
	v_lshl_add_u64 v[138:139], v[138:139], 0, s[18:19]
	s_lshl_b32 s18, s11, 21
	s_waitcnt lgkmcnt(7)
	v_lshlrev_b32_sdwa v72, v141, v153 dst_sel:DWORD dst_unused:UNUSED_PAD src0_sel:DWORD src1_sel:WORD_0
	s_waitcnt vmcnt(7)
	v_cvt_pk_f32_fp8_e32 v[36:37], v28
	v_cvt_pk_f32_fp8_sdwa v[38:39], v28 src0_sel:WORD_1
	v_cvt_pk_f32_fp8_e32 v[40:41], v29
	v_cvt_pk_f32_fp8_sdwa v[28:29], v29 src0_sel:WORD_1
	v_cvt_pk_f32_fp8_e32 v[42:43], v30
	v_cvt_pk_f32_fp8_sdwa v[44:45], v30 src0_sel:WORD_1
	v_cvt_pk_f32_fp8_e32 v[48:49], v31
	v_cvt_pk_f32_fp8_sdwa v[50:51], v31 src0_sel:WORD_1
	v_lshl_add_u64 v[162:163], v[32:33], 0, s[18:19]
	s_waitcnt vmcnt(6)
	v_cvt_pk_f32_fp8_e32 v[30:31], v20
	v_cvt_pk_f32_fp8_sdwa v[46:47], v20 src0_sel:WORD_1
	v_cvt_pk_f32_fp8_e32 v[52:53], v21
	v_cvt_pk_f32_fp8_sdwa v[54:55], v21 src0_sel:WORD_1
	v_cvt_pk_f32_fp8_e32 v[58:59], v22
	v_cvt_pk_f32_fp8_sdwa v[60:61], v22 src0_sel:WORD_1
	v_cvt_pk_f32_fp8_e32 v[68:69], v23
	v_cvt_pk_f32_fp8_sdwa v[70:71], v23 src0_sel:WORD_1
	v_lshl_add_u32 v154, s39, 8, v77
	v_or_b32_e32 v138, v138, v34
	v_lshl_add_u64 v[156:157], v[162:163], 0, v[72:73]
	s_waitcnt lgkmcnt(6)
	v_lshlrev_b32_sdwa v72, v141, v146 dst_sel:DWORD dst_unused:UNUSED_PAD src0_sel:DWORD src1_sel:WORD_0
	s_waitcnt vmcnt(5)
	v_cvt_pk_f32_fp8_e32 v[20:21], v24
	v_cvt_pk_f32_fp8_sdwa v[22:23], v24 src0_sel:WORD_1
	v_cvt_pk_f32_fp8_e32 v[56:57], v25
	v_cvt_pk_f32_fp8_sdwa v[24:25], v25 src0_sel:WORD_1
	v_cvt_pk_f32_fp8_e32 v[62:63], v26
	v_cvt_pk_f32_fp8_sdwa v[64:65], v26 src0_sel:WORD_1
	v_cvt_pk_f32_fp8_e32 v[78:79], v27
	v_cvt_pk_f32_fp8_sdwa v[80:81], v27 src0_sel:WORD_1
	ds_read_u16 v175, v173
	ds_read_u16 v179, v173 offset:16
	ds_read_u16 v181, v173 offset:32
	ds_read_u16 v183, v173 offset:48
	ds_read_u16 v185, v173 offset:64
	ds_read_u16 v187, v173 offset:80
	ds_read_u16 v189, v173 offset:96
	ds_read_u16 v191, v173 offset:112
	ds_read_u16 v160, v154
	ds_read_u16 v161, v154 offset:16
	ds_read_u16 v169, v154 offset:32
	ds_read_u16 v174, v154 offset:48
	ds_read_u16 v180, v154 offset:64
	ds_read_u16 v182, v154 offset:80
	ds_read_u16 v184, v154 offset:96
	ds_read_u16 v186, v154 offset:112
	ds_read_u16 v153, v173 offset:128
	ds_read_u16 v188, v154 offset:128
	ds_read_u16 v190, v154 offset:144
	ds_read_u16 v192, v154 offset:160
	ds_read_u16 v193, v154 offset:176
	ds_read_u16 v195, v154 offset:192
	ds_read_u16 v197, v154 offset:208
	ds_read_u16 v199, v154 offset:224
	ds_read_u16 v201, v154 offset:240
	v_lshlrev_b64 v[154:155], 2, v[138:139]
	v_lshl_add_u64 v[138:139], v[138:139], 1, s[64:65]
	v_lshl_add_u64 v[158:159], v[162:163], 0, v[72:73]
	s_waitcnt lgkmcnt(14)
	v_lshlrev_b32_sdwa v72, v141, v151 dst_sel:DWORD dst_unused:UNUSED_PAD src0_sel:DWORD src1_sel:WORD_0
	s_waitcnt vmcnt(4)
	v_cvt_pk_f32_fp8_e32 v[26:27], v12
	v_cvt_pk_f32_fp8_sdwa v[66:67], v12 src0_sel:WORD_1
	v_cvt_pk_f32_fp8_e32 v[82:83], v13
	v_cvt_pk_f32_fp8_sdwa v[12:13], v13 src0_sel:WORD_1
	v_cvt_pk_f32_fp8_e32 v[86:87], v14
	v_cvt_pk_f32_fp8_sdwa v[88:89], v14 src0_sel:WORD_1
	v_cvt_pk_f32_fp8_e32 v[92:93], v15
	v_cvt_pk_f32_fp8_sdwa v[94:95], v15 src0_sel:WORD_1
	ds_read_u16 v146, v173 offset:144
	ds_read_u16 v151, v173 offset:160
	v_lshl_add_u64 v[166:167], s[62:63], 0, v[154:155]
	global_load_dword v203, v[138:139], off
	v_lshlrev_b32_e32 v168, 16, v160
	v_lshlrev_b32_e32 v170, 16, v161
	v_lshl_add_u64 v[138:139], s[60:61], 0, v[154:155]
	global_load_dwordx4 v[154:157], v[156:157], off
	s_nop 0
	global_load_dwordx4 v[158:161], v[158:159], off
	v_lshl_add_u64 v[204:205], v[162:163], 0, v[72:73]
	v_lshlrev_b32_sdwa v72, v141, v152 dst_sel:DWORD dst_unused:UNUSED_PAD src0_sel:DWORD src1_sel:WORD_0
	v_lshlrev_b32_e32 v172, 16, v169
	v_pk_fma_f32 v[36:37], v[36:37], v[168:169], 0 op_sel_hi:[1,0,0]
	v_pk_fma_f32 v[38:39], v[38:39], v[168:169], 0 op_sel_hi:[1,0,0]
	v_pk_fma_f32 v[40:41], v[40:41], v[168:169], 0 op_sel_hi:[1,0,0]
	v_pk_fma_f32 v[28:29], v[28:29], v[168:169], 0 op_sel_hi:[1,0,0]
	v_pk_fma_f32 v[42:43], v[42:43], v[168:169], 0 op_sel_hi:[1,0,0]
	v_pk_fma_f32 v[44:45], v[44:45], v[168:169], 0 op_sel_hi:[1,0,0]
	v_pk_fma_f32 v[48:49], v[48:49], v[168:169], 0 op_sel_hi:[1,0,0]
	v_pk_fma_f32 v[50:51], v[50:51], v[168:169], 0 op_sel_hi:[1,0,0]
	v_lshl_add_u64 v[168:169], v[162:163], 0, v[72:73]
	v_lshlrev_b32_sdwa v72, v141, v147 dst_sel:DWORD dst_unused:UNUSED_PAD src0_sel:DWORD src1_sel:WORD_0
	s_waitcnt vmcnt(6)
	v_cvt_pk_f32_fp8_e32 v[14:15], v16
	v_cvt_pk_f32_fp8_sdwa v[84:85], v16 src0_sel:WORD_1
	v_cvt_pk_f32_fp8_e32 v[90:91], v17
	v_cvt_pk_f32_fp8_sdwa v[16:17], v17 src0_sel:WORD_1
	v_cvt_pk_f32_fp8_e32 v[96:97], v18
	v_cvt_pk_f32_fp8_sdwa v[98:99], v18 src0_sel:WORD_1
	v_cvt_pk_f32_fp8_e32 v[100:101], v19
	v_cvt_pk_f32_fp8_sdwa v[18:19], v19 src0_sel:WORD_1
	ds_read_u16 v152, v173 offset:176
	ds_read_u16 v147, v173 offset:192
	global_load_dwordx2 v[166:167], v[166:167], off
	v_pk_fma_f32 v[30:31], v[30:31], v[170:171], v[36:37] op_sel_hi:[1,0,1]
	v_pk_fma_f32 v[46:47], v[46:47], v[170:171], v[38:39] op_sel_hi:[1,0,1]
	v_pk_fma_f32 v[52:53], v[52:53], v[170:171], v[40:41] op_sel_hi:[1,0,1]
	v_pk_fma_f32 v[28:29], v[54:55], v[170:171], v[28:29] op_sel_hi:[1,0,1]
	v_pk_fma_f32 v[54:55], v[58:59], v[170:171], v[42:43] op_sel_hi:[1,0,1]
	v_pk_fma_f32 v[44:45], v[60:61], v[170:171], v[44:45] op_sel_hi:[1,0,1]
	v_pk_fma_f32 v[48:49], v[68:69], v[170:171], v[48:49] op_sel_hi:[1,0,1]
	v_pk_fma_f32 v[50:51], v[70:71], v[170:171], v[50:51] op_sel_hi:[1,0,1]
	global_load_dwordx4 v[36:39], v[204:205], off
	global_load_dwordx4 v[40:43], v[168:169], off
	v_lshl_add_u64 v[58:59], v[162:163], 0, v[72:73]
	v_lshlrev_b32_sdwa v72, v141, v148 dst_sel:DWORD dst_unused:UNUSED_PAD src0_sel:DWORD src1_sel:WORD_0
	s_waitcnt lgkmcnt(14)
	v_lshlrev_b32_e32 v174, 16, v174
	v_pk_fma_f32 v[20:21], v[20:21], v[172:173], v[30:31] op_sel_hi:[1,0,1]
	v_pk_fma_f32 v[22:23], v[22:23], v[172:173], v[46:47] op_sel_hi:[1,0,1]
	v_pk_fma_f32 v[30:31], v[56:57], v[172:173], v[52:53] op_sel_hi:[1,0,1]
	v_pk_fma_f32 v[24:25], v[24:25], v[172:173], v[28:29] op_sel_hi:[1,0,1]
	v_pk_fma_f32 v[28:29], v[62:63], v[172:173], v[54:55] op_sel_hi:[1,0,1]
	v_pk_fma_f32 v[44:45], v[64:65], v[172:173], v[44:45] op_sel_hi:[1,0,1]
	v_pk_fma_f32 v[46:47], v[78:79], v[172:173], v[48:49] op_sel_hi:[1,0,1]
	v_pk_fma_f32 v[48:49], v[80:81], v[172:173], v[50:51] op_sel_hi:[1,0,1]
	v_lshl_add_u64 v[50:51], v[162:163], 0, v[72:73]
	ds_read_u16 v148, v173 offset:208
	v_lshlrev_b32_sdwa v72, v141, v149 dst_sel:DWORD dst_unused:UNUSED_PAD src0_sel:DWORD src1_sel:WORD_0
	ds_read_u16 v149, v173 offset:224
	v_pk_fma_f32 v[20:21], v[26:27], v[174:175], v[20:21] op_sel_hi:[1,0,1]
	v_pk_fma_f32 v[26:27], v[82:83], v[174:175], v[30:31] op_sel_hi:[1,0,1]
	v_pk_fma_f32 v[12:13], v[12:13], v[174:175], v[24:25] op_sel_hi:[1,0,1]
	v_pk_fma_f32 v[24:25], v[86:87], v[174:175], v[28:29] op_sel_hi:[1,0,1]
	v_pk_fma_f32 v[28:29], v[88:89], v[174:175], v[44:45] op_sel_hi:[1,0,1]
	v_pk_fma_f32 v[30:31], v[92:93], v[174:175], v[46:47] op_sel_hi:[1,0,1]
	v_pk_fma_f32 v[52:53], v[94:95], v[174:175], v[48:49] op_sel_hi:[1,0,1]
	global_load_dwordx4 v[44:47], v[58:59], off
	s_nop 0
	global_load_dwordx4 v[48:51], v[50:51], off
	v_lshlrev_b32_e32 v180, 16, v180
	v_lshl_add_u64 v[54:55], v[162:163], 0, v[72:73]
	v_lshlrev_b32_sdwa v72, v141, v150 dst_sel:DWORD dst_unused:UNUSED_PAD src0_sel:DWORD src1_sel:WORD_0
	ds_read_u16 v150, v173 offset:240
	v_pk_fma_f32 v[12:13], v[16:17], v[180:181], v[12:13] op_sel_hi:[1,0,1]
	v_pk_fma_f32 v[16:17], v[96:97], v[180:181], v[24:25] op_sel_hi:[1,0,1]
	v_pk_fma_f32 v[24:25], v[98:99], v[180:181], v[28:29] op_sel_hi:[1,0,1]
	v_pk_fma_f32 v[18:19], v[18:19], v[180:181], v[52:53] op_sel_hi:[1,0,1]
	v_lshl_add_u64 v[28:29], v[162:163], 0, v[72:73]
	global_load_dwordx4 v[52:55], v[54:55], off
	s_nop 0
	global_load_dwordx4 v[56:59], v[28:29], off
	s_waitcnt vmcnt(12)
	v_cvt_pk_f32_fp8_e32 v[102:103], v4
	v_cvt_pk_f32_fp8_sdwa v[104:105], v4 src0_sel:WORD_1
	v_cvt_pk_f32_fp8_e32 v[106:107], v5
	v_cvt_pk_f32_fp8_sdwa v[4:5], v5 src0_sel:WORD_1
	v_cvt_pk_f32_fp8_e32 v[108:109], v6
	v_cvt_pk_f32_fp8_sdwa v[110:111], v6 src0_sel:WORD_1
	v_cvt_pk_f32_fp8_e32 v[114:115], v7
	v_cvt_pk_f32_fp8_sdwa v[116:117], v7 src0_sel:WORD_1
	s_waitcnt vmcnt(11)
	v_cvt_pk_f32_fp8_e32 v[6:7], v8
	v_cvt_pk_f32_fp8_sdwa v[112:113], v8 src0_sel:WORD_1
	v_cvt_pk_f32_fp8_e32 v[118:119], v9
	v_cvt_pk_f32_fp8_sdwa v[8:9], v9 src0_sel:WORD_1
	v_cvt_pk_f32_fp8_e32 v[120:121], v10
	v_cvt_pk_f32_fp8_sdwa v[122:123], v10 src0_sel:WORD_1
	v_cvt_pk_f32_fp8_e32 v[124:125], v11
	v_cvt_pk_f32_fp8_sdwa v[10:11], v11 src0_sel:WORD_1
	s_waitcnt vmcnt(10)
	v_cvt_pk_f32_fp8_e32 v[126:127], v0
	v_cvt_pk_f32_fp8_sdwa v[128:129], v0 src0_sel:WORD_1
	v_cvt_pk_f32_fp8_e32 v[130:131], v1
	v_cvt_pk_f32_fp8_sdwa v[0:1], v1 src0_sel:WORD_1
	s_and_b32 s18, s3, 0xe00000
	v_pk_fma_f32 v[22:23], v[66:67], v[174:175], v[22:23] op_sel_hi:[1,0,1]
	v_cvt_pk_f32_fp8_e32 v[132:133], v2
	v_cvt_pk_f32_fp8_sdwa v[134:135], v2 src0_sel:WORD_1
	v_cvt_pk_f32_fp8_e32 v[136:137], v3
	v_cvt_pk_f32_fp8_sdwa v[2:3], v3 src0_sel:WORD_1
	v_lshl_add_u64 v[164:165], v[32:33], 0, s[18:19]
	v_lshlrev_b32_e32 v182, 16, v182
	v_pk_fma_f32 v[14:15], v[14:15], v[180:181], v[20:21] op_sel_hi:[1,0,1]
	v_pk_fma_f32 v[20:21], v[84:85], v[180:181], v[22:23] op_sel_hi:[1,0,1]
	v_pk_fma_f32 v[22:23], v[90:91], v[180:181], v[26:27] op_sel_hi:[1,0,1]
	v_pk_fma_f32 v[26:27], v[100:101], v[180:181], v[30:31] op_sel_hi:[1,0,1]
	v_lshlrev_b32_e32 v72, 7, v175
	v_lshlrev_b32_e32 v184, 16, v184
	v_pk_fma_f32 v[4:5], v[4:5], v[182:183], v[12:13] op_sel_hi:[1,0,1]
	v_pk_fma_f32 v[12:13], v[108:109], v[182:183], v[16:17] op_sel_hi:[1,0,1]
	v_pk_fma_f32 v[16:17], v[110:111], v[182:183], v[24:25] op_sel_hi:[1,0,1]
	v_pk_fma_f32 v[24:25], v[114:115], v[182:183], v[26:27] op_sel_hi:[1,0,1]
	v_pk_fma_f32 v[18:19], v[116:117], v[182:183], v[18:19] op_sel_hi:[1,0,1]
	v_lshl_add_u64 v[26:27], v[164:165], 0, v[72:73]
	v_lshlrev_b32_e32 v72, 7, v179
	s_waitcnt lgkmcnt(14)
	v_lshlrev_b32_e32 v186, 16, v186
	v_pk_fma_f32 v[4:5], v[8:9], v[184:185], v[4:5] op_sel_hi:[1,0,1]
	v_pk_fma_f32 v[10:11], v[10:11], v[184:185], v[18:19] op_sel_hi:[1,0,1]
	v_lshl_add_u64 v[18:19], v[164:165], 0, v[72:73]
	v_lshlrev_b32_e32 v72, 7, v181
	v_pk_fma_f32 v[14:15], v[102:103], v[182:183], v[14:15] op_sel_hi:[1,0,1]
	v_pk_fma_f32 v[20:21], v[104:105], v[182:183], v[20:21] op_sel_hi:[1,0,1]
	v_pk_fma_f32 v[22:23], v[106:107], v[182:183], v[22:23] op_sel_hi:[1,0,1]
	v_pk_fma_f32 v[66:67], v[0:1], v[186:187], v[4:5] op_sel_hi:[1,0,1]
	v_lshl_add_u64 v[0:1], v[164:165], 0, v[72:73]
	v_lshlrev_b32_e32 v72, 7, v183
	v_pk_fma_f32 v[6:7], v[6:7], v[184:185], v[14:15] op_sel_hi:[1,0,1]
	v_pk_fma_f32 v[14:15], v[112:113], v[184:185], v[20:21] op_sel_hi:[1,0,1]
	v_pk_fma_f32 v[20:21], v[118:119], v[184:185], v[22:23] op_sel_hi:[1,0,1]
	v_pk_fma_f32 v[8:9], v[120:121], v[184:185], v[12:13] op_sel_hi:[1,0,1]
	v_pk_fma_f32 v[12:13], v[122:123], v[184:185], v[16:17] op_sel_hi:[1,0,1]
	v_pk_fma_f32 v[80:81], v[2:3], v[186:187], v[10:11] op_sel_hi:[1,0,1]
	v_lshl_add_u64 v[2:3], v[164:165], 0, v[72:73]
	v_lshlrev_b32_e32 v72, 7, v185
	v_pk_fma_f32 v[16:17], v[124:125], v[184:185], v[24:25] op_sel_hi:[1,0,1]
	v_pk_fma_f32 v[62:63], v[128:129], v[186:187], v[14:15] op_sel_hi:[1,0,1]
	v_pk_fma_f32 v[64:65], v[130:131], v[186:187], v[20:21] op_sel_hi:[1,0,1]
	v_pk_fma_f32 v[70:71], v[134:135], v[186:187], v[12:13] op_sel_hi:[1,0,1]
	global_load_dwordx4 v[28:31], v[26:27], off
	global_load_dwordx4 v[20:23], v[18:19], off
	s_nop 0
	global_load_dwordx4 v[24:27], v[0:1], off
	global_load_dwordx4 v[12:15], v[2:3], off
	v_lshl_add_u64 v[0:1], v[164:165], 0, v[72:73]
	v_lshlrev_b32_e32 v72, 7, v187
	v_lshl_add_u64 v[2:3], v[164:165], 0, v[72:73]
	v_lshlrev_b32_e32 v72, 7, v189
	v_pk_fma_f32 v[60:61], v[126:127], v[186:187], v[6:7] op_sel_hi:[1,0,1]
	v_pk_fma_f32 v[78:79], v[136:137], v[186:187], v[16:17] op_sel_hi:[1,0,1]
	global_load_dwordx4 v[16:19], v[0:1], off
	global_load_dwordx4 v[4:7], v[2:3], off
	v_lshl_add_u64 v[0:1], v[164:165], 0, v[72:73]
	v_lshlrev_b32_e32 v72, 7, v191
	v_lshl_add_u64 v[2:3], v[164:165], 0, v[72:73]
	v_pk_fma_f32 v[68:69], v[132:133], v[186:187], v[8:9] op_sel_hi:[1,0,1]
	global_load_dwordx4 v[8:11], v[0:1], off
	s_nop 0
	global_load_dwordx4 v[0:3], v[2:3], off
	s_waitcnt vmcnt(16)
	v_cvt_pk_f32_fp8_e32 v[82:83], v154
	v_cvt_pk_f32_fp8_sdwa v[84:85], v154 src0_sel:WORD_1
	v_cvt_pk_f32_fp8_e32 v[86:87], v155
	v_cvt_pk_f32_fp8_sdwa v[88:89], v155 src0_sel:WORD_1
	v_cvt_pk_f32_fp8_e32 v[90:91], v156
	v_cvt_pk_f32_fp8_sdwa v[92:93], v156 src0_sel:WORD_1
	v_cvt_pk_f32_fp8_e32 v[94:95], v157
	v_cvt_pk_f32_fp8_sdwa v[96:97], v157 src0_sel:WORD_1
	s_waitcnt vmcnt(15)
	v_cvt_pk_f32_fp8_e32 v[100:101], v158
	v_cvt_pk_f32_fp8_sdwa v[102:103], v158 src0_sel:WORD_1
	v_cvt_pk_f32_fp8_e32 v[104:105], v159
	v_cvt_pk_f32_fp8_sdwa v[106:107], v159 src0_sel:WORD_1
	v_cvt_pk_f32_fp8_e32 v[108:109], v160
	v_cvt_pk_f32_fp8_sdwa v[110:111], v160 src0_sel:WORD_1
	v_cvt_pk_f32_fp8_e32 v[112:113], v161
	v_cvt_pk_f32_fp8_sdwa v[114:115], v161 src0_sel:WORD_1
	s_waitcnt vmcnt(13)
	v_cvt_pk_f32_fp8_e32 v[116:117], v36
	v_cvt_pk_f32_fp8_sdwa v[118:119], v36 src0_sel:WORD_1
	v_cvt_pk_f32_fp8_e32 v[120:121], v37
	v_cvt_pk_f32_fp8_sdwa v[36:37], v37 src0_sel:WORD_1
	v_cvt_pk_f32_fp8_e32 v[122:123], v38
	v_cvt_pk_f32_fp8_sdwa v[124:125], v38 src0_sel:WORD_1
	v_cvt_pk_f32_fp8_e32 v[126:127], v39
	v_cvt_pk_f32_fp8_sdwa v[38:39], v39 src0_sel:WORD_1
	v_lshlrev_b32_e32 v188, 16, v188
	s_waitcnt vmcnt(12)
	v_cvt_pk_f32_fp8_e32 v[128:129], v40
	v_cvt_pk_f32_fp8_sdwa v[130:131], v40 src0_sel:WORD_1
	v_cvt_pk_f32_fp8_e32 v[132:133], v41
	v_cvt_pk_f32_fp8_sdwa v[40:41], v41 src0_sel:WORD_1
	v_cvt_pk_f32_fp8_e32 v[134:135], v42
	v_cvt_pk_f32_fp8_sdwa v[136:137], v42 src0_sel:WORD_1
	v_cvt_pk_f32_fp8_e32 v[154:155], v43
	v_cvt_pk_f32_fp8_sdwa v[42:43], v43 src0_sel:WORD_1
	s_waitcnt lgkmcnt(13)
	v_lshlrev_b32_e32 v190, 16, v190
	v_pk_fma_f32 v[60:61], v[82:83], v[188:189], v[60:61] op_sel_hi:[1,0,1]
	v_pk_fma_f32 v[62:63], v[84:85], v[188:189], v[62:63] op_sel_hi:[1,0,1]
	v_pk_fma_f32 v[64:65], v[86:87], v[188:189], v[64:65] op_sel_hi:[1,0,1]
	v_pk_fma_f32 v[66:67], v[88:89], v[188:189], v[66:67] op_sel_hi:[1,0,1]
	v_pk_fma_f32 v[68:69], v[90:91], v[188:189], v[68:69] op_sel_hi:[1,0,1]
	v_pk_fma_f32 v[70:71], v[92:93], v[188:189], v[70:71] op_sel_hi:[1,0,1]
	v_pk_fma_f32 v[78:79], v[94:95], v[188:189], v[78:79] op_sel_hi:[1,0,1]
	v_pk_fma_f32 v[80:81], v[96:97], v[188:189], v[80:81] op_sel_hi:[1,0,1]
	s_waitcnt vmcnt(11)
	v_cvt_pk_f32_fp8_e32 v[82:83], v44
	v_cvt_pk_f32_fp8_sdwa v[84:85], v44 src0_sel:WORD_1
	v_cvt_pk_f32_fp8_e32 v[86:87], v45
	v_cvt_pk_f32_fp8_sdwa v[44:45], v45 src0_sel:WORD_1
	v_cvt_pk_f32_fp8_e32 v[88:89], v46
	v_cvt_pk_f32_fp8_sdwa v[90:91], v46 src0_sel:WORD_1
	v_cvt_pk_f32_fp8_e32 v[92:93], v47
	v_cvt_pk_f32_fp8_sdwa v[46:47], v47 src0_sel:WORD_1
	s_waitcnt lgkmcnt(12)
	v_lshlrev_b32_e32 v192, 16, v192
	v_pk_fma_f32 v[60:61], v[100:101], v[190:191], v[60:61] op_sel_hi:[1,0,1]
	v_pk_fma_f32 v[62:63], v[102:103], v[190:191], v[62:63] op_sel_hi:[1,0,1]
	v_pk_fma_f32 v[64:65], v[104:105], v[190:191], v[64:65] op_sel_hi:[1,0,1]
	v_pk_fma_f32 v[66:67], v[106:107], v[190:191], v[66:67] op_sel_hi:[1,0,1]
	v_pk_fma_f32 v[68:69], v[108:109], v[190:191], v[68:69] op_sel_hi:[1,0,1]
	v_pk_fma_f32 v[70:71], v[110:111], v[190:191], v[70:71] op_sel_hi:[1,0,1]
	v_pk_fma_f32 v[78:79], v[112:113], v[190:191], v[78:79] op_sel_hi:[1,0,1]
	v_pk_fma_f32 v[80:81], v[114:115], v[190:191], v[80:81] op_sel_hi:[1,0,1]
	s_waitcnt vmcnt(10)
	v_cvt_pk_f32_fp8_e32 v[94:95], v48
	v_cvt_pk_f32_fp8_sdwa v[96:97], v48 src0_sel:WORD_1
	v_cvt_pk_f32_fp8_e32 v[100:101], v49
	v_cvt_pk_f32_fp8_sdwa v[48:49], v49 src0_sel:WORD_1
	v_cvt_pk_f32_fp8_e32 v[102:103], v50
	v_cvt_pk_f32_fp8_sdwa v[104:105], v50 src0_sel:WORD_1
	v_cvt_pk_f32_fp8_e32 v[106:107], v51
	v_cvt_pk_f32_fp8_sdwa v[50:51], v51 src0_sel:WORD_1
	s_waitcnt lgkmcnt(11)
	v_lshlrev_b32_e32 v194, 16, v193
	v_pk_fma_f32 v[60:61], v[116:117], v[192:193], v[60:61] op_sel_hi:[1,0,1]
	v_pk_fma_f32 v[62:63], v[118:119], v[192:193], v[62:63] op_sel_hi:[1,0,1]
	v_pk_fma_f32 v[64:65], v[120:121], v[192:193], v[64:65] op_sel_hi:[1,0,1]
	v_pk_fma_f32 v[36:37], v[36:37], v[192:193], v[66:67] op_sel_hi:[1,0,1]
	v_pk_fma_f32 v[66:67], v[122:123], v[192:193], v[68:69] op_sel_hi:[1,0,1]
	v_pk_fma_f32 v[68:69], v[124:125], v[192:193], v[70:71] op_sel_hi:[1,0,1]
	v_pk_fma_f32 v[70:71], v[126:127], v[192:193], v[78:79] op_sel_hi:[1,0,1]
	v_pk_fma_f32 v[38:39], v[38:39], v[192:193], v[80:81] op_sel_hi:[1,0,1]
	s_waitcnt vmcnt(9)
	v_cvt_pk_f32_fp8_e32 v[78:79], v52
	v_cvt_pk_f32_fp8_sdwa v[80:81], v52 src0_sel:WORD_1
	v_cvt_pk_f32_fp8_e32 v[108:109], v53
	v_cvt_pk_f32_fp8_sdwa v[52:53], v53 src0_sel:WORD_1
	v_cvt_pk_f32_fp8_e32 v[110:111], v54
	v_cvt_pk_f32_fp8_sdwa v[112:113], v54 src0_sel:WORD_1
	v_cvt_pk_f32_fp8_e32 v[114:115], v55
	v_cvt_pk_f32_fp8_sdwa v[54:55], v55 src0_sel:WORD_1
	s_waitcnt lgkmcnt(10)
	v_lshlrev_b32_e32 v196, 16, v195
	v_pk_fma_f32 v[60:61], v[128:129], v[194:195], v[60:61] op_sel_hi:[1,0,1]
	v_pk_fma_f32 v[62:63], v[130:131], v[194:195], v[62:63] op_sel_hi:[1,0,1]
	v_pk_fma_f32 v[64:65], v[132:133], v[194:195], v[64:65] op_sel_hi:[1,0,1]
	v_pk_fma_f32 v[36:37], v[40:41], v[194:195], v[36:37] op_sel_hi:[1,0,1]
	v_pk_fma_f32 v[40:41], v[134:135], v[194:195], v[66:67] op_sel_hi:[1,0,1]
	v_pk_fma_f32 v[66:67], v[136:137], v[194:195], v[68:69] op_sel_hi:[1,0,1]
	v_pk_fma_f32 v[68:69], v[154:155], v[194:195], v[70:71] op_sel_hi:[1,0,1]
	v_pk_fma_f32 v[38:39], v[42:43], v[194:195], v[38:39] op_sel_hi:[1,0,1]
	s_waitcnt vmcnt(8)
	v_cvt_pk_f32_fp8_e32 v[42:43], v56
	v_cvt_pk_f32_fp8_sdwa v[70:71], v56 src0_sel:WORD_1
	v_cvt_pk_f32_fp8_e32 v[116:117], v57
	v_cvt_pk_f32_fp8_sdwa v[56:57], v57 src0_sel:WORD_1
	v_cvt_pk_f32_fp8_e32 v[118:119], v58
	v_cvt_pk_f32_fp8_sdwa v[120:121], v58 src0_sel:WORD_1
	v_cvt_pk_f32_fp8_e32 v[122:123], v59
	v_cvt_pk_f32_fp8_sdwa v[58:59], v59 src0_sel:WORD_1
	s_waitcnt lgkmcnt(9)
	v_lshlrev_b32_e32 v198, 16, v197
	v_pk_fma_f32 v[60:61], v[82:83], v[196:197], v[60:61] op_sel_hi:[1,0,1]
	v_pk_fma_f32 v[62:63], v[84:85], v[196:197], v[62:63] op_sel_hi:[1,0,1]
	v_pk_fma_f32 v[64:65], v[86:87], v[196:197], v[64:65] op_sel_hi:[1,0,1]
	v_pk_fma_f32 v[36:37], v[44:45], v[196:197], v[36:37] op_sel_hi:[1,0,1]
	v_pk_fma_f32 v[40:41], v[88:89], v[196:197], v[40:41] op_sel_hi:[1,0,1]
	v_pk_fma_f32 v[44:45], v[90:91], v[196:197], v[66:67] op_sel_hi:[1,0,1]
	v_pk_fma_f32 v[66:67], v[92:93], v[196:197], v[68:69] op_sel_hi:[1,0,1]
	v_pk_fma_f32 v[38:39], v[46:47], v[196:197], v[38:39] op_sel_hi:[1,0,1]
	s_waitcnt lgkmcnt(8)
	v_lshlrev_b32_e32 v200, 16, v199
	v_pk_fma_f32 v[46:47], v[94:95], v[198:199], v[60:61] op_sel_hi:[1,0,1]
	v_pk_fma_f32 v[60:61], v[96:97], v[198:199], v[62:63] op_sel_hi:[1,0,1]
	v_pk_fma_f32 v[62:63], v[100:101], v[198:199], v[64:65] op_sel_hi:[1,0,1]
	v_pk_fma_f32 v[36:37], v[48:49], v[198:199], v[36:37] op_sel_hi:[1,0,1]
	v_pk_fma_f32 v[40:41], v[102:103], v[198:199], v[40:41] op_sel_hi:[1,0,1]
	v_pk_fma_f32 v[44:45], v[104:105], v[198:199], v[44:45] op_sel_hi:[1,0,1]
	v_pk_fma_f32 v[48:49], v[106:107], v[198:199], v[66:67] op_sel_hi:[1,0,1]
	v_pk_fma_f32 v[38:39], v[50:51], v[198:199], v[38:39] op_sel_hi:[1,0,1]
	s_waitcnt lgkmcnt(7)
	v_lshlrev_b32_e32 v202, 16, v201
	v_pk_fma_f32 v[46:47], v[78:79], v[200:201], v[46:47] op_sel_hi:[1,0,1]
	v_pk_fma_f32 v[50:51], v[80:81], v[200:201], v[60:61] op_sel_hi:[1,0,1]
	v_pk_fma_f32 v[60:61], v[108:109], v[200:201], v[62:63] op_sel_hi:[1,0,1]
	v_pk_fma_f32 v[36:37], v[52:53], v[200:201], v[36:37] op_sel_hi:[1,0,1]
	v_pk_fma_f32 v[40:41], v[110:111], v[200:201], v[40:41] op_sel_hi:[1,0,1]
	v_pk_fma_f32 v[44:45], v[112:113], v[200:201], v[44:45] op_sel_hi:[1,0,1]
	v_pk_fma_f32 v[48:49], v[114:115], v[200:201], v[48:49] op_sel_hi:[1,0,1]
	v_pk_fma_f32 v[38:39], v[54:55], v[200:201], v[38:39] op_sel_hi:[1,0,1]
	v_pk_fma_f32 v[42:43], v[42:43], v[202:203], v[46:47] op_sel_hi:[1,0,1]
	v_pk_fma_f32 v[46:47], v[70:71], v[202:203], v[50:51] op_sel_hi:[1,0,1]
	v_pk_fma_f32 v[50:51], v[116:117], v[202:203], v[60:61] op_sel_hi:[1,0,1]
	v_pk_fma_f32 v[36:37], v[56:57], v[202:203], v[36:37] op_sel_hi:[1,0,1]
	v_pk_fma_f32 v[40:41], v[118:119], v[202:203], v[40:41] op_sel_hi:[1,0,1]
	v_pk_fma_f32 v[44:45], v[120:121], v[202:203], v[44:45] op_sel_hi:[1,0,1]
	v_pk_fma_f32 v[48:49], v[122:123], v[202:203], v[48:49] op_sel_hi:[1,0,1]
	v_pk_fma_f32 v[38:39], v[58:59], v[202:203], v[38:39] op_sel_hi:[1,0,1]
	v_cndmask_b32_e64 v52, v42, v40, s[4:5]
	v_cndmask_b32_e64 v53, v43, v41, s[4:5]
	v_cndmask_b32_e64 v41, v41, v43, s[4:5]
	v_cndmask_b32_e64 v40, v40, v42, s[4:5]
	v_cndmask_b32_e64 v54, v46, v44, s[4:5]
	v_cndmask_b32_e64 v55, v47, v45, s[4:5]
	v_cndmask_b32_e64 v43, v45, v47, s[4:5]
	v_cndmask_b32_e64 v42, v44, v46, s[4:5]
	v_cndmask_b32_e64 v56, v50, v48, s[4:5]
	v_cndmask_b32_e64 v57, v51, v49, s[4:5]
	v_cndmask_b32_e64 v45, v49, v51, s[4:5]
	v_cndmask_b32_e64 v44, v48, v50, s[4:5]
	v_cndmask_b32_e64 v50, v36, v38, s[4:5]
	v_cndmask_b32_e64 v51, v37, v39, s[4:5]
	v_cndmask_b32_e64 v37, v39, v37, s[4:5]
	v_cndmask_b32_e64 v36, v38, v36, s[4:5]
	ds_bpermute_b32 v38, v35, v52
	ds_bpermute_b32 v39, v35, v53
	ds_bpermute_b32 v46, v35, v54
	ds_bpermute_b32 v47, v35, v55
	ds_bpermute_b32 v48, v35, v56
	ds_bpermute_b32 v49, v35, v57
	ds_bpermute_b32 v50, v35, v50
	ds_bpermute_b32 v51, v35, v51
	s_waitcnt lgkmcnt(6)
	v_pk_add_f32 v[38:39], v[40:41], v[38:39]
	s_waitcnt lgkmcnt(4)
	v_pk_add_f32 v[40:41], v[42:43], v[46:47]
	s_waitcnt lgkmcnt(2)
	v_pk_add_f32 v[42:43], v[44:45], v[48:49]
	v_lshlrev_b32_e32 v98, 16, v203
	s_waitcnt lgkmcnt(0)
	v_pk_add_f32 v[36:37], v[36:37], v[50:51]
	v_cndmask_b32_e32 v44, v38, v42, vcc
	v_cndmask_b32_e32 v45, v39, v43, vcc
	v_cndmask_b32_e32 v39, v43, v39, vcc
	v_cndmask_b32_e32 v38, v42, v38, vcc
	v_cndmask_b32_e32 v42, v40, v36, vcc
	v_cndmask_b32_e32 v43, v41, v37, vcc
	v_cndmask_b32_e32 v37, v37, v41, vcc
	v_cndmask_b32_e32 v36, v36, v40, vcc
	ds_bpermute_b32 v40, v144, v44
	ds_bpermute_b32 v41, v144, v45
	ds_bpermute_b32 v42, v144, v42
	ds_bpermute_b32 v43, v144, v43
	v_and_b32_e32 v99, 0xffff0000, v203
	s_add_i32 s7, s41, 1
	s_waitcnt lgkmcnt(2)
	v_pk_add_f32 v[38:39], v[38:39], v[40:41]
	s_addk_i32 s6, 0x80
	s_waitcnt lgkmcnt(0)
	v_pk_add_f32 v[36:37], v[36:37], v[42:43]
	s_add_i32 s3, s3, 0x10000
	v_cndmask_b32_e64 v40, v38, v36, s[0:1]
	v_cndmask_b32_e64 v41, v39, v37, s[0:1]
	v_cndmask_b32_e64 v37, v37, v39, s[0:1]
	v_cndmask_b32_e64 v36, v36, v38, s[0:1]
	v_mov_b32_dpp v38, v40 row_ror:8 row_mask:0xf bank_mask:0xf bound_ctrl:1
	v_mov_b32_dpp v39, v41 row_ror:8 row_mask:0xf bank_mask:0xf bound_ctrl:1
	v_pk_add_f32 v[166:167], v[166:167], s[100:101] op_sel_hi:[1,0] neg_lo:[0,1] neg_hi:[0,1]
	s_nop 0
	v_pk_mul_f32 v[166:167], v[166:167], s[100:101] op_sel:[0,1]
	s_nop 0
	v_pk_fma_f32 v[166:167], v[246:247], v[166:167], v[248:249]
	s_nop 0
	v_pk_fma_f32 v[98:99], v[166:167], s[58:59], v[98:99] op_sel_hi:[1,0,1]
	v_pk_add_f32 v[36:37], v[36:37], v[38:39]
	s_mov_b32 s41, s7
	s_cmpk_eq_i32 s7, 0x100
	v_pk_add_f32 v[36:37], v[98:99], v[36:37]
	global_store_dwordx2 v[138:139], v[36:37], off
	s_cbranch_scc0 .LBB0_1139
	s_waitcnt vmcnt(0)
	s_barrier
	v_lshlrev_b64 v[0:1], 12, v[74:75]
	v_lshl_add_u64 v[0:1], s[60:61], 0, v[0:1]
	v_mov_b32_e32 v77, v73
	v_lshl_add_u64 v[64:65], v[0:1], 0, v[76:77]
	v_lshl_add_u64 v[66:67], s[90:91], 0, v[76:77]
	v_lshl_add_u64 v[68:69], s[68:69], 0, v[76:77]
	s_mov_b64 s[100:101], 0x1000
	v_lshl_add_u64 v[64:65], v[64:65], 0, s[100:101]
	global_load_dwordx4 v[206:209], v[66:67], off
	global_load_dwordx4 v[210:213], v[66:67], off offset:1024
	global_load_dwordx4 v[214:217], v[66:67], off offset:2048
	global_load_dwordx4 v[218:221], v[66:67], off offset:3072
	global_load_dwordx4 v[222:225], v[68:69], off
	global_load_dwordx4 v[226:229], v[68:69], off offset:1024
	global_load_dwordx4 v[230:233], v[68:69], off offset:2048
	global_load_dwordx4 v[234:237], v[68:69], off offset:3072
	global_load_dwordx4 v[0:3], v[64:65], off offset:-4096
	global_load_dwordx4 v[4:7], v[64:65], off offset:-3072
	global_load_dwordx4 v[8:11], v[64:65], off offset:-2048
	global_load_dwordx4 v[12:15], v[64:65], off offset:-1024
	global_load_dwordx4 v[40:43], v[66:67], off
	global_load_dwordx4 v[40:43], v[66:67], off
	global_load_dwordx4 v[40:43], v[66:67], off
	global_load_dwordx4 v[40:43], v[66:67], off
	s_mov_b32 s0, 0
